# FFN-in epilogue: the vmcnt(0) at the head of each of the 16 predicated store blocks (which also drained the previous block's store) replaced by one wait per channel-half after the conv-weight loads, o
# baseline (speedup 1.0000x reference)
.LBB0_939:
	v_add_f32_e32 v191, v191, v198
	v_fmamk_f32 v191, v191, 0x3a800000, v243
	s_ashr_i32 s1, s0, 31
	s_lshl_b64 s[0:1], s[0:1], 12
	s_nop 1
	s_waitcnt lgkmcnt(3)
	v_mov_b32_dpp v170, v114 row_shr:1 row_mask:0xf bank_mask:0xf
	s_waitcnt lgkmcnt(2)
	v_mov_b32_dpp v162, v122 row_shr:1 row_mask:0xf bank_mask:0xf
	s_waitcnt lgkmcnt(1)
	v_mov_b32_dpp v174, v118 row_shr:1 row_mask:0xf bank_mask:0xf
	s_nop 1
	s_waitcnt lgkmcnt(0)
	v_mov_b32_dpp v166, v126 row_shr:1 row_mask:0xf bank_mask:0xf
	v_mov_b32_dpp v171, v115 row_shr:1 row_mask:0xf bank_mask:0xf
	s_nop 1
	v_mov_b32_dpp v163, v123 row_shr:1 row_mask:0xf bank_mask:0xf
	v_mov_b32_dpp v175, v119 row_shr:1 row_mask:0xf bank_mask:0xf
	s_nop 1
	v_mov_b32_dpp v167, v127 row_shr:1 row_mask:0xf bank_mask:0xf
	v_mov_b32_dpp v172, v116 row_shr:1 row_mask:0xf bank_mask:0xf
	s_nop 1
	s_movk_i32 s10, 0x1000
	v_cmp_gt_i32_e64 s[46:47], s10, v190
	v_mov_b32_dpp v164, v124 row_shr:1 row_mask:0xf bank_mask:0xf
	v_rsq_f32_e32 v198, v191
	s_nop 0
	v_cmp_lt_i32_e32 vcc, 1, v199
	v_pk_mul_f32 v[96:97], v[96:97], v[198:199] op_sel_hi:[1,0]
	v_pk_mul_f32 v[94:95], v[94:95], v[198:199] op_sel_hi:[1,0]
	v_pk_mul_f32 v[92:93], v[92:93], v[198:199] op_sel_hi:[1,0]
	v_pk_mul_f32 v[90:91], v[90:91], v[198:199] op_sel_hi:[1,0]
	v_mov_b32_dpp v176, v120 row_shr:1 row_mask:0xf bank_mask:0xf
	v_mov_b32_dpp v168, v128 row_shr:1 row_mask:0xf bank_mask:0xf
	v_mov_b32_dpp v173, v117 row_shr:1 row_mask:0xf bank_mask:0xf
	v_mov_b32_dpp v165, v125 row_shr:1 row_mask:0xf bank_mask:0xf
	v_mov_b32_dpp v177, v121 row_shr:1 row_mask:0xf bank_mask:0xf
	v_mov_b32_dpp v169, v129 row_shr:1 row_mask:0xf bank_mask:0xf
	s_and_b64 s[24:25], vcc, s[46:47]
	v_ashrrev_i32_e32 v191, 31, v190
	s_waitcnt vmcnt(0)
	s_and_saveexec_b64 s[10:11], s[24:25]
	s_cbranch_execz .LBB0_941
	v_pk_fma_f32 v[174:175], v[146:147], v[174:175], v[158:159]
	v_pk_fma_f32 v[170:171], v[138:139], v[170:171], v[142:143]
	v_pk_fma_f32 v[174:175], v[150:151], v[166:167], v[174:175]
	v_pk_fma_f32 v[170:171], v[130:131], v[162:163], v[170:171]
	v_pk_fma_f32 v[174:175], v[90:91], v[154:155], v[174:175]
	v_pk_fma_f32 v[170:171], v[94:95], v[134:135], v[170:171]
	v_mul_f32_e32 v210, 0xbfb8aa3b, v174
	v_pk_mul_f32 v[170:171], v[170:171], v[174:175]
	v_mul_f32_e32 v174, 0xbfb8aa3b, v175
	v_exp_f32_e32 v174, v174
	v_pk_fma_f32 v[172:173], v[140:141], v[172:173], v[144:145]
	v_exp_f32_e32 v210, v210
	v_pk_fma_f32 v[172:173], v[132:133], v[164:165], v[172:173]
	v_add_f32_e32 v174, 1.0, v174
	v_rcp_f32_e32 v215, v174
	v_pk_fma_f32 v[174:175], v[148:149], v[176:177], v[160:161]
	v_pk_fma_f32 v[172:173], v[96:97], v[136:137], v[172:173]
	v_pk_fma_f32 v[174:175], v[152:153], v[168:169], v[174:175]
	v_add_f32_e32 v210, 1.0, v210
	v_pk_fma_f32 v[174:175], v[92:93], v[156:157], v[174:175]
	v_rcp_f32_e32 v214, v210
	v_mul_f32_e32 v176, 0xbfb8aa3b, v174
	v_pk_mul_f32 v[172:173], v[172:173], v[174:175]
	v_mul_f32_e32 v174, 0xbfb8aa3b, v175
	v_exp_f32_e32 v176, v176
	v_exp_f32_e32 v174, v174
	v_readlane_b32 s26, v251, 45
	v_readlane_b32 s27, v251, 46
	v_add_f32_e32 v176, 1.0, v176
	v_add_f32_e32 v174, 1.0, v174
	v_rcp_f32_e32 v176, v176
	v_rcp_f32_e32 v177, v174
	v_lshl_add_u64 v[174:175], s[0:1], 0, v[190:191]
	v_pk_mul_f32 v[170:171], v[170:171], v[214:215]
	v_pk_mul_f32 v[172:173], v[172:173], v[176:177]
	v_mov_b64_e32 v[176:177], s[26:27]
	v_mad_u64_u32 v[176:177], s[26:27], v174, s54, v[176:177]
	v_mad_i32_i24 v177, v175, s54, v177
	v_lshl_add_u64 v[174:175], v[192:193], 1, v[176:177]
	v_cvt_pk_bf16_f32 v170, v170, v171
	v_cvt_pk_bf16_f32 v171, v172, v173
	global_store_dwordx2 v[174:175], v[170:171], off
.LBB0_941:
	s_or_b64 exec, exec, s[10:11]
	v_add_f32_e32 v170, v208, v209
	v_fmamk_f32 v170, v170, 0x3a800000, v243
	s_nop 1
	s_movk_i32 s10, 0x1000
	v_rsq_f32_e32 v172, v170
	s_nop 0
	v_or_b32_e32 v170, 1, v199
	v_add_u32_e32 v170, s31, v170
	v_cmp_lt_i32_e32 vcc, 0, v199
	v_cmp_gt_i32_e64 s[46:47], s10, v170
	v_pk_mul_f32 v[84:85], v[84:85], v[172:173] op_sel_hi:[1,0]
	v_pk_mul_f32 v[82:83], v[82:83], v[172:173] op_sel_hi:[1,0]
	v_pk_mul_f32 v[80:81], v[80:81], v[172:173] op_sel_hi:[1,0]
	v_pk_mul_f32 v[78:79], v[78:79], v[172:173] op_sel_hi:[1,0]
	s_and_b64 s[26:27], vcc, s[46:47]
	v_ashrrev_i32_e32 v171, 31, v170
	s_and_saveexec_b64 s[10:11], s[26:27]
	s_cbranch_execz .LBB0_943
	v_pk_fma_f32 v[166:167], v[146:147], v[166:167], v[158:159]
	v_pk_fma_f32 v[162:163], v[138:139], v[162:163], v[142:143]
	v_pk_fma_f32 v[166:167], v[90:91], v[150:151], v[166:167]
	v_pk_fma_f32 v[162:163], v[94:95], v[130:131], v[162:163]
	v_pk_fma_f32 v[166:167], v[78:79], v[154:155], v[166:167]
	v_pk_fma_f32 v[162:163], v[82:83], v[134:135], v[162:163]
	v_mul_f32_e32 v173, 0xbfb8aa3b, v166
	v_pk_mul_f32 v[162:163], v[162:163], v[166:167]
	v_mul_f32_e32 v166, 0xbfb8aa3b, v167
	v_exp_f32_e32 v166, v166
	v_pk_fma_f32 v[164:165], v[140:141], v[164:165], v[144:145]
	v_exp_f32_e32 v173, v173
	v_pk_fma_f32 v[164:165], v[96:97], v[132:133], v[164:165]
	v_add_f32_e32 v166, 1.0, v166
	v_rcp_f32_e32 v175, v166
	v_pk_fma_f32 v[166:167], v[148:149], v[168:169], v[160:161]
	v_pk_fma_f32 v[164:165], v[84:85], v[136:137], v[164:165]
	v_pk_fma_f32 v[166:167], v[92:93], v[152:153], v[166:167]
	v_add_f32_e32 v173, 1.0, v173
	v_pk_fma_f32 v[166:167], v[80:81], v[156:157], v[166:167]
	v_rcp_f32_e32 v174, v173
	v_mul_f32_e32 v168, 0xbfb8aa3b, v166
	v_pk_mul_f32 v[164:165], v[164:165], v[166:167]
	v_mul_f32_e32 v166, 0xbfb8aa3b, v167
	v_exp_f32_e32 v168, v168
	v_exp_f32_e32 v166, v166
	v_readlane_b32 s38, v251, 45
	v_readlane_b32 s39, v251, 46
	v_add_f32_e32 v168, 1.0, v168
	v_add_f32_e32 v166, 1.0, v166
	v_rcp_f32_e32 v168, v168
	v_rcp_f32_e32 v169, v166
	v_lshl_add_u64 v[166:167], s[0:1], 0, v[170:171]
	v_pk_mul_f32 v[162:163], v[162:163], v[174:175]
	v_pk_mul_f32 v[164:165], v[164:165], v[168:169]
	v_mov_b64_e32 v[168:169], s[38:39]
	v_mad_u64_u32 v[168:169], s[38:39], v166, s54, v[168:169]
	v_mad_i32_i24 v169, v167, s54, v169
	v_lshl_add_u64 v[166:167], v[192:193], 1, v[168:169]
	v_cvt_pk_bf16_f32 v162, v162, v163
	v_cvt_pk_bf16_f32 v163, v164, v165
	global_store_dwordx2 v[166:167], v[162:163], off

.LBB0_945:
	s_or_b64 exec, exec, s[38:39]
	v_or_b32_e32 v162, 2, v199
	v_add_u32_e32 v162, s31, v162
	s_movk_i32 s15, 0x1000
	v_cmp_lt_i32_e32 vcc, -1, v199
	v_cmp_gt_i32_e64 s[46:47], s15, v162
	s_and_b64 s[38:39], vcc, s[46:47]
	v_ashrrev_i32_e32 v163, 31, v162
	s_and_saveexec_b64 s[40:41], s[38:39]
	s_cbranch_execz .LBB0_947
	v_pk_fma_f32 v[90:91], v[146:147], v[90:91], v[158:159]
	v_pk_fma_f32 v[96:97], v[140:141], v[96:97], v[144:145]
	v_pk_fma_f32 v[90:91], v[150:151], v[174:175], v[90:91]
	v_pk_fma_f32 v[96:97], v[132:133], v[166:167], v[96:97]
	v_pk_fma_f32 v[90:91], v[118:119], v[154:155], v[90:91]
	v_pk_fma_f32 v[92:93], v[148:149], v[92:93], v[160:161]
	v_mul_f32_e32 v166, 0xbfb8aa3b, v91
	v_exp_f32_e32 v166, v166
	v_pk_fma_f32 v[92:93], v[152:153], v[168:169], v[92:93]
	v_pk_fma_f32 v[94:95], v[138:139], v[94:95], v[142:143]
	v_pk_fma_f32 v[92:93], v[120:121], v[156:157], v[92:93]
	v_mul_f32_e32 v173, 0xbfb8aa3b, v90
	v_pk_fma_f32 v[94:95], v[130:131], v[164:165], v[94:95]
	v_add_f32_e32 v164, 1.0, v166
	v_mul_f32_e32 v165, 0xbfb8aa3b, v92
	v_mul_f32_e32 v166, 0xbfb8aa3b, v93
	v_exp_f32_e32 v173, v173
	v_exp_f32_e32 v165, v165
	v_exp_f32_e32 v166, v166
	v_rcp_f32_e32 v169, v164
	v_add_f32_e32 v168, 1.0, v173
	v_add_f32_e32 v164, 1.0, v165
	v_add_f32_e32 v165, 1.0, v166
	v_rcp_f32_e32 v168, v168
	v_rcp_f32_e32 v164, v164
	v_rcp_f32_e32 v165, v165
	v_readlane_b32 s46, v251, 45
	v_pk_fma_f32 v[96:97], v[116:117], v[136:137], v[96:97]
	v_pk_fma_f32 v[94:95], v[114:115], v[134:135], v[94:95]
	v_readlane_b32 s47, v251, 46
	v_pk_mul_f32 v[92:93], v[96:97], v[92:93]
	v_pk_mul_f32 v[90:91], v[94:95], v[90:91]
	v_lshl_add_u64 v[94:95], s[0:1], 0, v[162:163]
	v_mov_b64_e32 v[96:97], s[46:47]
	v_mad_u64_u32 v[96:97], s[46:47], v94, s54, v[96:97]
	v_pk_mul_f32 v[90:91], v[90:91], v[168:169]
	v_pk_mul_f32 v[92:93], v[92:93], v[164:165]
	v_mad_i32_i24 v97, v95, s54, v97
	v_lshl_add_u64 v[94:95], v[192:193], 1, v[96:97]
	v_cvt_pk_bf16_f32 v90, v90, v91
	v_cvt_pk_bf16_f32 v91, v92, v93
	global_store_dwordx2 v[94:95], v[90:91], off
.LBB0_947:
	s_or_b64 exec, exec, s[40:41]
	v_or_b32_e32 v90, 3, v199
	v_add_u32_e32 v164, s31, v90
	v_cmp_gt_i32_e64 s[46:47], s15, v164
	s_and_b64 s[92:93], vcc, s[46:47]
	v_ashrrev_i32_e32 v165, 31, v164
	s_and_saveexec_b64 s[40:41], s[92:93]
	s_cbranch_execz .LBB0_949
	v_cndmask_b32_e64 v79, v79, 0, s[10:11]
	v_cndmask_b32_e64 v78, v78, 0, s[10:11]
	v_cndmask_b32_e64 v81, v81, 0, s[10:11]
	v_cndmask_b32_e64 v80, v80, 0, s[10:11]
	v_pk_fma_f32 v[78:79], v[78:79], v[146:147], v[158:159]
	v_pk_fma_f32 v[80:81], v[80:81], v[148:149], v[160:161]
	v_pk_fma_f32 v[78:79], v[118:119], v[150:151], v[78:79]
	v_pk_fma_f32 v[80:81], v[120:121], v[152:153], v[80:81]
	v_pk_fma_f32 v[78:79], v[126:127], v[154:155], v[78:79]
	v_pk_fma_f32 v[80:81], v[128:129], v[156:157], v[80:81]
	v_mul_f32_e32 v90, 0xbfb8aa3b, v78
	v_mul_f32_e32 v91, 0xbfb8aa3b, v79
	v_mul_f32_e32 v92, 0xbfb8aa3b, v80
	v_mul_f32_e32 v93, 0xbfb8aa3b, v81
	v_exp_f32_e32 v90, v90
	v_exp_f32_e32 v91, v91
	v_exp_f32_e32 v92, v92
	v_exp_f32_e32 v93, v93
	v_cndmask_b32_e64 v85, v85, 0, s[10:11]
	v_cndmask_b32_e64 v84, v84, 0, s[10:11]
	v_cndmask_b32_e64 v83, v83, 0, s[10:11]
	v_cndmask_b32_e64 v82, v82, 0, s[10:11]
	v_add_f32_e32 v90, 1.0, v90
	v_pk_fma_f32 v[82:83], v[82:83], v[138:139], v[142:143]
	v_pk_fma_f32 v[84:85], v[84:85], v[140:141], v[144:145]
	v_add_f32_e32 v91, 1.0, v91
	v_add_f32_e32 v92, 1.0, v92
	v_add_f32_e32 v93, 1.0, v93
	v_rcp_f32_e32 v90, v90
	v_pk_fma_f32 v[84:85], v[116:117], v[132:133], v[84:85]
	v_pk_fma_f32 v[82:83], v[114:115], v[130:131], v[82:83]
	v_rcp_f32_e32 v91, v91
	v_rcp_f32_e32 v92, v92
	v_rcp_f32_e32 v93, v93
	v_readlane_b32 s46, v251, 45
	v_pk_fma_f32 v[82:83], v[122:123], v[134:135], v[82:83]
	v_pk_fma_f32 v[84:85], v[124:125], v[136:137], v[84:85]
	v_readlane_b32 s47, v251, 46
	v_pk_mul_f32 v[80:81], v[84:85], v[80:81]
	v_pk_mul_f32 v[78:79], v[82:83], v[78:79]
	v_lshl_add_u64 v[82:83], s[0:1], 0, v[164:165]
	v_mov_b64_e32 v[84:85], s[46:47]
	v_mad_u64_u32 v[84:85], s[46:47], v82, s54, v[84:85]
	v_pk_mul_f32 v[78:79], v[78:79], v[90:91]
	v_pk_mul_f32 v[80:81], v[80:81], v[92:93]
	v_mad_i32_i24 v85, v83, s54, v85
	v_lshl_add_u64 v[82:83], v[192:193], 1, v[84:85]
	v_cvt_pk_bf16_f32 v78, v78, v79
	v_cvt_pk_bf16_f32 v79, v80, v81
	global_store_dwordx2 v[82:83], v[78:79], off

.LBB0_951:
	v_add_f32_e32 v114, v206, v207
	v_fmamk_f32 v114, v114, 0x3a800000, v243
	s_waitcnt lgkmcnt(3)
	v_mov_b32_dpp v90, v106 row_shr:1 row_mask:0xf bank_mask:0xf
	s_waitcnt lgkmcnt(2)
	v_mov_b32_dpp v78, v102 row_shr:1 row_mask:0xf bank_mask:0xf
	s_nop 1
	s_waitcnt lgkmcnt(1)
	v_mov_b32_dpp v94, v110 row_shr:1 row_mask:0xf bank_mask:0xf
	s_waitcnt lgkmcnt(0)
	v_mov_b32_dpp v82, v98 row_shr:1 row_mask:0xf bank_mask:0xf
	v_mov_b32_dpp v91, v107 row_shr:1 row_mask:0xf bank_mask:0xf
	s_nop 1
	v_mov_b32_dpp v79, v103 row_shr:1 row_mask:0xf bank_mask:0xf
	v_mov_b32_dpp v95, v111 row_shr:1 row_mask:0xf bank_mask:0xf
	s_nop 1
	v_mov_b32_dpp v83, v99 row_shr:1 row_mask:0xf bank_mask:0xf
	v_mov_b32_dpp v92, v108 row_shr:1 row_mask:0xf bank_mask:0xf
	s_nop 1
	v_mov_b32_dpp v80, v104 row_shr:1 row_mask:0xf bank_mask:0xf
	v_mov_b32_dpp v96, v112 row_shr:1 row_mask:0xf bank_mask:0xf
	s_nop 1
	v_mov_b32_dpp v84, v100 row_shr:1 row_mask:0xf bank_mask:0xf
	v_mov_b32_dpp v93, v109 row_shr:1 row_mask:0xf bank_mask:0xf
	v_mov_b32_dpp v81, v105 row_shr:1 row_mask:0xf bank_mask:0xf
	v_rsq_f32_e32 v122, v114
	s_nop 0
	v_add_u32_e32 v115, 0x80, v199
	v_add_u32_e32 v114, s31, v115
	v_cmp_lt_i32_e32 vcc, 1, v115
	v_cmp_gt_i32_e64 s[48:49], s15, v114
	v_pk_mul_f32 v[72:73], v[72:73], v[122:123] op_sel_hi:[1,0]
	v_pk_mul_f32 v[70:71], v[70:71], v[122:123] op_sel_hi:[1,0]
	v_pk_mul_f32 v[68:69], v[68:69], v[122:123] op_sel_hi:[1,0]
	v_pk_mul_f32 v[66:67], v[66:67], v[122:123] op_sel_hi:[1,0]
	v_mov_b32_dpp v97, v113 row_shr:1 row_mask:0xf bank_mask:0xf
	v_mov_b32_dpp v85, v101 row_shr:1 row_mask:0xf bank_mask:0xf
	s_and_b64 s[54:55], vcc, s[48:49]
	v_ashrrev_i32_e32 v115, 31, v114
	s_and_saveexec_b64 s[40:41], s[54:55]
	s_cbranch_execz .LBB0_953
	v_pk_fma_f32 v[94:95], v[146:147], v[94:95], v[158:159]
	v_pk_fma_f32 v[90:91], v[138:139], v[90:91], v[142:143]
	v_pk_fma_f32 v[94:95], v[150:151], v[82:83], v[94:95]
	v_pk_fma_f32 v[90:91], v[130:131], v[78:79], v[90:91]
	v_pk_fma_f32 v[94:95], v[66:67], v[154:155], v[94:95]
	v_pk_fma_f32 v[90:91], v[70:71], v[134:135], v[90:91]
	v_mul_f32_e32 v116, 0xbfb8aa3b, v94
	v_pk_mul_f32 v[90:91], v[90:91], v[94:95]
	v_mul_f32_e32 v94, 0xbfb8aa3b, v95
	v_exp_f32_e32 v94, v94
	v_pk_fma_f32 v[92:93], v[140:141], v[92:93], v[144:145]
	v_exp_f32_e32 v116, v116
	v_pk_fma_f32 v[92:93], v[132:133], v[80:81], v[92:93]
	v_add_f32_e32 v94, 1.0, v94
	v_rcp_f32_e32 v117, v94
	v_pk_fma_f32 v[94:95], v[148:149], v[96:97], v[160:161]
	v_pk_fma_f32 v[92:93], v[72:73], v[136:137], v[92:93]
	v_pk_fma_f32 v[94:95], v[152:153], v[84:85], v[94:95]
	v_add_f32_e32 v116, 1.0, v116
	v_pk_fma_f32 v[94:95], v[68:69], v[156:157], v[94:95]
	v_rcp_f32_e32 v116, v116
	v_mul_f32_e32 v96, 0xbfb8aa3b, v94
	v_pk_mul_f32 v[92:93], v[92:93], v[94:95]
	v_mul_f32_e32 v94, 0xbfb8aa3b, v95
	v_exp_f32_e32 v96, v96
	v_exp_f32_e32 v94, v94
	v_readlane_b32 s48, v251, 45
	v_readlane_b32 s49, v251, 46
	v_add_f32_e32 v96, 1.0, v96
	v_add_f32_e32 v94, 1.0, v94
	v_rcp_f32_e32 v96, v96
	v_rcp_f32_e32 v97, v94
	v_lshl_add_u64 v[94:95], s[0:1], 0, v[114:115]
	s_movk_i32 s15, 0x1600
	v_pk_mul_f32 v[90:91], v[90:91], v[116:117]
	v_pk_mul_f32 v[92:93], v[92:93], v[96:97]
	v_mov_b64_e32 v[96:97], s[48:49]
	v_mad_u64_u32 v[96:97], s[48:49], v94, s15, v[96:97]
	v_mad_i32_i24 v97, v95, s15, v97
	v_lshl_add_u64 v[94:95], v[192:193], 1, v[96:97]
	v_cvt_pk_bf16_f32 v90, v90, v91
	v_cvt_pk_bf16_f32 v91, v92, v93
	global_store_dwordx2 v[94:95], v[90:91], off
.LBB0_953:
	s_or_b64 exec, exec, s[40:41]
	v_add_f32_e32 v90, v204, v205
	v_fmamk_f32 v90, v90, 0x3a800000, v243
	s_movk_i32 s15, 0x1000
	s_nop 0
	v_rsq_f32_e32 v124, v90
	s_nop 0
	v_add_u32_e32 v90, 0x81, v199
	v_add_u32_e32 v116, s31, v90
	v_cmp_lt_i32_e32 vcc, 1, v90
	v_cmp_gt_i32_e64 s[48:49], s15, v116
	v_pk_mul_f32 v[52:53], v[52:53], v[124:125] op_sel_hi:[1,0]
	v_pk_mul_f32 v[50:51], v[50:51], v[124:125] op_sel_hi:[1,0]
	v_pk_mul_f32 v[48:49], v[48:49], v[124:125] op_sel_hi:[1,0]
	v_pk_mul_f32 v[46:47], v[46:47], v[124:125] op_sel_hi:[1,0]
	s_and_b64 s[40:41], vcc, s[48:49]
	v_ashrrev_i32_e32 v117, 31, v116
	s_and_saveexec_b64 s[48:49], s[40:41]
	s_cbranch_execz .LBB0_955
	v_pk_fma_f32 v[82:83], v[146:147], v[82:83], v[158:159]
	v_pk_fma_f32 v[78:79], v[138:139], v[78:79], v[142:143]
	v_pk_fma_f32 v[82:83], v[66:67], v[150:151], v[82:83]
	v_pk_fma_f32 v[78:79], v[70:71], v[130:131], v[78:79]
	v_pk_fma_f32 v[82:83], v[46:47], v[154:155], v[82:83]
	v_pk_fma_f32 v[78:79], v[50:51], v[134:135], v[78:79]
	v_mul_f32_e32 v90, 0xbfb8aa3b, v82
	v_pk_mul_f32 v[78:79], v[78:79], v[82:83]
	v_mul_f32_e32 v82, 0xbfb8aa3b, v83
	v_exp_f32_e32 v82, v82
	v_pk_fma_f32 v[80:81], v[140:141], v[80:81], v[144:145]
	v_exp_f32_e32 v90, v90
	v_pk_fma_f32 v[80:81], v[72:73], v[132:133], v[80:81]
	v_add_f32_e32 v82, 1.0, v82
	v_rcp_f32_e32 v91, v82
	v_pk_fma_f32 v[82:83], v[148:149], v[84:85], v[160:161]
	v_pk_fma_f32 v[80:81], v[52:53], v[136:137], v[80:81]
	v_pk_fma_f32 v[82:83], v[68:69], v[152:153], v[82:83]
	v_add_f32_e32 v90, 1.0, v90
	v_pk_fma_f32 v[82:83], v[48:49], v[156:157], v[82:83]
	v_rcp_f32_e32 v90, v90
	v_mul_f32_e32 v84, 0xbfb8aa3b, v82
	v_pk_mul_f32 v[80:81], v[80:81], v[82:83]
	v_mul_f32_e32 v82, 0xbfb8aa3b, v83
	v_exp_f32_e32 v84, v84
	v_exp_f32_e32 v82, v82
	v_readlane_b32 s68, v251, 45
	v_readlane_b32 s69, v251, 46
	v_add_f32_e32 v84, 1.0, v84
	v_add_f32_e32 v82, 1.0, v82
	v_rcp_f32_e32 v84, v84
	v_rcp_f32_e32 v85, v82
	v_lshl_add_u64 v[82:83], s[0:1], 0, v[116:117]
	s_movk_i32 s15, 0x1600
	v_pk_mul_f32 v[78:79], v[78:79], v[90:91]
	v_pk_mul_f32 v[80:81], v[80:81], v[84:85]
	v_mov_b64_e32 v[84:85], s[68:69]
	v_mad_u64_u32 v[84:85], s[94:95], v82, s15, v[84:85]
	v_mad_i32_i24 v85, v83, s15, v85
	v_lshl_add_u64 v[82:83], v[192:193], 1, v[84:85]
	v_cvt_pk_bf16_f32 v78, v78, v79
	v_cvt_pk_bf16_f32 v79, v80, v81
	global_store_dwordx2 v[82:83], v[78:79], off

.LBB0_957:
	s_or_b64 exec, exec, s[48:49]
	v_add_u32_e32 v90, 0x82, v199
	v_add_u32_e32 v118, s31, v90
	s_movk_i32 s15, 0x1000
	v_cmp_lt_i32_e32 vcc, 1, v90
	v_cmp_gt_i32_e64 s[48:49], s15, v118
	s_and_b64 s[94:95], vcc, s[48:49]
	v_ashrrev_i32_e32 v119, 31, v118
	s_and_saveexec_b64 s[48:49], s[94:95]
	s_cbranch_execz .LBB0_959
	v_pk_fma_f32 v[66:67], v[146:147], v[66:67], v[158:159]
	v_pk_fma_f32 v[72:73], v[140:141], v[72:73], v[144:145]
	v_pk_fma_f32 v[66:67], v[150:151], v[84:85], v[66:67]
	v_pk_fma_f32 v[72:73], v[132:133], v[80:81], v[72:73]
	v_pk_fma_f32 v[66:67], v[110:111], v[154:155], v[66:67]
	v_pk_fma_f32 v[68:69], v[148:149], v[68:69], v[160:161]
	v_mul_f32_e32 v80, 0xbfb8aa3b, v67
	v_exp_f32_e32 v80, v80
	v_pk_fma_f32 v[68:69], v[152:153], v[82:83], v[68:69]
	v_pk_fma_f32 v[70:71], v[138:139], v[70:71], v[142:143]
	v_pk_fma_f32 v[68:69], v[112:113], v[156:157], v[68:69]
	v_mul_f32_e32 v84, 0xbfb8aa3b, v66
	v_pk_fma_f32 v[70:71], v[130:131], v[78:79], v[70:71]
	v_add_f32_e32 v78, 1.0, v80
	v_mul_f32_e32 v79, 0xbfb8aa3b, v68
	v_mul_f32_e32 v80, 0xbfb8aa3b, v69
	v_exp_f32_e32 v84, v84
	v_exp_f32_e32 v79, v79
	v_exp_f32_e32 v80, v80
	v_rcp_f32_e32 v83, v78
	v_add_f32_e32 v82, 1.0, v84
	v_add_f32_e32 v78, 1.0, v79
	v_add_f32_e32 v79, 1.0, v80
	v_rcp_f32_e32 v82, v82
	v_rcp_f32_e32 v78, v78
	v_rcp_f32_e32 v79, v79
	v_readlane_b32 s68, v251, 45
	v_pk_fma_f32 v[72:73], v[108:109], v[136:137], v[72:73]
	v_pk_fma_f32 v[70:71], v[106:107], v[134:135], v[70:71]
	v_readlane_b32 s69, v251, 46
	v_pk_mul_f32 v[68:69], v[72:73], v[68:69]
	v_pk_mul_f32 v[66:67], v[70:71], v[66:67]
	v_lshl_add_u64 v[70:71], s[0:1], 0, v[118:119]
	v_mov_b64_e32 v[72:73], s[68:69]
	s_movk_i32 s15, 0x1600
	v_mad_u64_u32 v[72:73], vcc, v70, s15, v[72:73]
	v_pk_mul_f32 v[66:67], v[66:67], v[82:83]
	v_pk_mul_f32 v[68:69], v[68:69], v[78:79]
	v_mad_i32_i24 v73, v71, s15, v73
	v_lshl_add_u64 v[70:71], v[192:193], 1, v[72:73]
	v_cvt_pk_bf16_f32 v66, v66, v67
	v_cvt_pk_bf16_f32 v67, v68, v69
	global_store_dwordx2 v[70:71], v[66:67], off
.LBB0_959:
	s_or_b64 exec, exec, s[48:49]
	v_add_u32_e32 v66, 0x83, v199
	v_add_u32_e32 v120, s31, v66
	s_movk_i32 s15, 0x1000
	v_cmp_lt_i32_e32 vcc, 1, v66
	v_cmp_gt_i32_e64 s[48:49], s15, v120
	s_and_b64 s[48:49], vcc, s[48:49]
	v_ashrrev_i32_e32 v121, 31, v120
	s_and_saveexec_b64 vcc, s[48:49]
	s_cbranch_execz .LBB0_961
	v_cndmask_b32_e64 v47, v47, 0, s[12:13]
	v_cndmask_b32_e64 v46, v46, 0, s[12:13]
	v_cndmask_b32_e64 v49, v49, 0, s[12:13]
	v_cndmask_b32_e64 v48, v48, 0, s[12:13]
	v_pk_fma_f32 v[46:47], v[46:47], v[146:147], v[158:159]
	v_pk_fma_f32 v[48:49], v[48:49], v[148:149], v[160:161]
	v_pk_fma_f32 v[46:47], v[110:111], v[150:151], v[46:47]
	v_pk_fma_f32 v[48:49], v[112:113], v[152:153], v[48:49]
	v_pk_fma_f32 v[46:47], v[98:99], v[154:155], v[46:47]
	v_pk_fma_f32 v[48:49], v[100:101], v[156:157], v[48:49]
	v_mul_f32_e32 v66, 0xbfb8aa3b, v46
	v_mul_f32_e32 v67, 0xbfb8aa3b, v47
	v_mul_f32_e32 v68, 0xbfb8aa3b, v48
	v_mul_f32_e32 v69, 0xbfb8aa3b, v49
	v_exp_f32_e32 v66, v66
	v_exp_f32_e32 v67, v67
	v_exp_f32_e32 v68, v68
	v_exp_f32_e32 v69, v69
	v_cndmask_b32_e64 v53, v53, 0, s[12:13]
	v_cndmask_b32_e64 v52, v52, 0, s[12:13]
	v_cndmask_b32_e64 v51, v51, 0, s[12:13]
	v_cndmask_b32_e64 v50, v50, 0, s[12:13]
	v_add_f32_e32 v66, 1.0, v66
	v_pk_fma_f32 v[50:51], v[50:51], v[138:139], v[142:143]
	v_pk_fma_f32 v[52:53], v[52:53], v[140:141], v[144:145]
	v_add_f32_e32 v67, 1.0, v67
	v_add_f32_e32 v68, 1.0, v68
	v_add_f32_e32 v69, 1.0, v69
	v_rcp_f32_e32 v66, v66
	v_pk_fma_f32 v[52:53], v[108:109], v[132:133], v[52:53]
	v_pk_fma_f32 v[50:51], v[106:107], v[130:131], v[50:51]
	v_rcp_f32_e32 v67, v67
	v_rcp_f32_e32 v68, v68
	v_rcp_f32_e32 v69, v69
	v_readlane_b32 s68, v251, 45
	v_pk_fma_f32 v[50:51], v[102:103], v[134:135], v[50:51]
	v_pk_fma_f32 v[52:53], v[104:105], v[136:137], v[52:53]
	v_readlane_b32 s69, v251, 46
	v_pk_mul_f32 v[48:49], v[52:53], v[48:49]
	v_pk_mul_f32 v[46:47], v[50:51], v[46:47]
	v_lshl_add_u64 v[50:51], s[0:1], 0, v[120:121]
	v_mov_b64_e32 v[52:53], s[68:69]
	s_movk_i32 s15, 0x1600
	v_mad_u64_u32 v[52:53], s[68:69], v50, s15, v[52:53]
	v_pk_mul_f32 v[46:47], v[46:47], v[66:67]
	v_pk_mul_f32 v[48:49], v[48:49], v[68:69]
	v_mad_i32_i24 v53, v51, s15, v53
	v_lshl_add_u64 v[50:51], v[192:193], 1, v[52:53]
	v_cvt_pk_bf16_f32 v46, v46, v47
	v_cvt_pk_bf16_f32 v47, v48, v49
	global_store_dwordx2 v[50:51], v[46:47], off

.LBB0_964:
	v_mov_b32_e32 v199, v198
	v_mov_b32_e32 v126, v198
	v_mov_b32_e32 v127, v198
	v_pk_mul_f32 v[32:33], v[32:33], v[126:127]
	v_pk_mul_f32 v[30:31], v[30:31], v[198:199]
	v_pk_mul_f32 v[28:29], v[28:29], v[126:127]
	v_pk_mul_f32 v[26:27], v[26:27], v[198:199]
	s_waitcnt lgkmcnt(3)
	v_mov_b32_dpp v106, v42 row_shr:1 row_mask:0xf bank_mask:0xf
	s_waitcnt lgkmcnt(2)
	v_mov_b32_dpp v98, v58 row_shr:1 row_mask:0xf bank_mask:0xf
	s_waitcnt lgkmcnt(1)
	v_mov_b32_dpp v110, v54 row_shr:1 row_mask:0xf bank_mask:0xf
	s_waitcnt lgkmcnt(0)
	v_mov_b32_dpp v102, v62 row_shr:1 row_mask:0xf bank_mask:0xf
	v_mov_b32_dpp v107, v43 row_shr:1 row_mask:0xf bank_mask:0xf
	v_mov_b32_dpp v99, v59 row_shr:1 row_mask:0xf bank_mask:0xf
	v_mov_b32_dpp v111, v55 row_shr:1 row_mask:0xf bank_mask:0xf
	v_mov_b32_dpp v103, v63 row_shr:1 row_mask:0xf bank_mask:0xf
	v_mov_b32_dpp v108, v44 row_shr:1 row_mask:0xf bank_mask:0xf
	v_mov_b32_dpp v100, v60 row_shr:1 row_mask:0xf bank_mask:0xf
	v_mov_b32_dpp v112, v56 row_shr:1 row_mask:0xf bank_mask:0xf
	v_mov_b32_dpp v104, v64 row_shr:1 row_mask:0xf bank_mask:0xf
	v_mov_b32_dpp v109, v45 row_shr:1 row_mask:0xf bank_mask:0xf
	v_mov_b32_dpp v101, v61 row_shr:1 row_mask:0xf bank_mask:0xf
	v_mov_b32_dpp v113, v57 row_shr:1 row_mask:0xf bank_mask:0xf
	v_mov_b32_dpp v105, v65 row_shr:1 row_mask:0xf bank_mask:0xf
	s_waitcnt vmcnt(0)
	s_and_saveexec_b64 s[44:45], s[24:25]
	s_cbranch_execz .LBB0_966
	v_pk_fma_f32 v[110:111], v[78:79], v[110:111], v[94:95]
	v_pk_fma_f32 v[106:107], v[66:67], v[106:107], v[70:71]
	v_pk_fma_f32 v[110:111], v[82:83], v[102:103], v[110:111]
	v_pk_fma_f32 v[106:107], v[50:51], v[98:99], v[106:107]
	v_pk_fma_f32 v[110:111], v[26:27], v[90:91], v[110:111]
	v_pk_fma_f32 v[106:107], v[30:31], v[46:47], v[106:107]
	v_mul_f32_e32 v125, 0xbfb8aa3b, v110
	v_pk_mul_f32 v[106:107], v[106:107], v[110:111]
	v_mul_f32_e32 v110, 0xbfb8aa3b, v111
	v_exp_f32_e32 v110, v110
	v_pk_fma_f32 v[108:109], v[68:69], v[108:109], v[72:73]
	v_exp_f32_e32 v125, v125
	v_pk_fma_f32 v[108:109], v[52:53], v[100:101], v[108:109]
	v_add_f32_e32 v110, 1.0, v110
	v_rcp_f32_e32 v127, v110
	v_pk_fma_f32 v[110:111], v[80:81], v[112:113], v[96:97]
	v_pk_fma_f32 v[108:109], v[32:33], v[48:49], v[108:109]
	v_pk_fma_f32 v[110:111], v[84:85], v[104:105], v[110:111]
	v_add_f32_e32 v125, 1.0, v125
	v_pk_fma_f32 v[110:111], v[28:29], v[92:93], v[110:111]
	v_rcp_f32_e32 v126, v125
	v_mul_f32_e32 v112, 0xbfb8aa3b, v110
	v_pk_mul_f32 v[108:109], v[108:109], v[110:111]
	v_mul_f32_e32 v110, 0xbfb8aa3b, v111
	v_exp_f32_e32 v112, v112
	v_exp_f32_e32 v110, v110
	v_readlane_b32 s24, v251, 45
	v_readlane_b32 s25, v251, 46
	v_add_f32_e32 v112, 1.0, v112
	v_add_f32_e32 v110, 1.0, v110
	v_rcp_f32_e32 v112, v112
	v_rcp_f32_e32 v113, v110
	v_lshl_add_u64 v[110:111], s[0:1], 0, v[190:191]
	s_movk_i32 s15, 0x1600
	v_pk_mul_f32 v[106:107], v[106:107], v[126:127]
	v_pk_mul_f32 v[108:109], v[108:109], v[112:113]
	v_mov_b64_e32 v[112:113], s[24:25]
	v_mad_u64_u32 v[112:113], s[24:25], v110, s15, v[112:113]
	v_mad_i32_i24 v113, v111, s15, v113
	v_lshl_add_u64 v[110:111], v[192:193], 1, v[112:113]
	v_cvt_pk_bf16_f32 v106, v106, v107
	v_cvt_pk_bf16_f32 v107, v108, v109
	global_store_dwordx2 v[110:111], v[106:107], off offset:8
.LBB0_966:
	s_or_b64 exec, exec, s[44:45]
	v_mov_b32_e32 v173, v172
	v_mov_b32_e32 v106, v172
	v_mov_b32_e32 v107, v172
	v_pk_mul_f32 v[24:25], v[24:25], v[106:107]
	v_pk_mul_f32 v[22:23], v[22:23], v[172:173]
	v_pk_mul_f32 v[20:21], v[20:21], v[106:107]
	v_pk_mul_f32 v[18:19], v[18:19], v[172:173]
	s_and_saveexec_b64 s[24:25], s[26:27]
	s_cbranch_execz .LBB0_968
	v_pk_fma_f32 v[102:103], v[78:79], v[102:103], v[94:95]
	v_pk_fma_f32 v[98:99], v[66:67], v[98:99], v[70:71]
	v_pk_fma_f32 v[102:103], v[26:27], v[82:83], v[102:103]
	v_pk_fma_f32 v[98:99], v[30:31], v[50:51], v[98:99]
	v_pk_fma_f32 v[102:103], v[18:19], v[90:91], v[102:103]
	v_pk_fma_f32 v[98:99], v[22:23], v[46:47], v[98:99]
	v_mul_f32_e32 v106, 0xbfb8aa3b, v102
	v_pk_mul_f32 v[98:99], v[98:99], v[102:103]
	v_mul_f32_e32 v102, 0xbfb8aa3b, v103
	v_exp_f32_e32 v102, v102
	v_pk_fma_f32 v[100:101], v[68:69], v[100:101], v[72:73]
	v_exp_f32_e32 v106, v106
	v_pk_fma_f32 v[100:101], v[32:33], v[52:53], v[100:101]
	v_add_f32_e32 v102, 1.0, v102
	v_rcp_f32_e32 v107, v102
	v_pk_fma_f32 v[102:103], v[80:81], v[104:105], v[96:97]
	v_pk_fma_f32 v[100:101], v[24:25], v[48:49], v[100:101]
	v_pk_fma_f32 v[102:103], v[28:29], v[84:85], v[102:103]
	v_add_f32_e32 v106, 1.0, v106
	v_pk_fma_f32 v[102:103], v[20:21], v[92:93], v[102:103]
	v_rcp_f32_e32 v106, v106
	v_mul_f32_e32 v104, 0xbfb8aa3b, v102
	v_pk_mul_f32 v[100:101], v[100:101], v[102:103]
	v_mul_f32_e32 v102, 0xbfb8aa3b, v103
	v_exp_f32_e32 v104, v104
	v_exp_f32_e32 v102, v102
	v_readlane_b32 s26, v251, 45
	v_readlane_b32 s27, v251, 46
	v_add_f32_e32 v104, 1.0, v104
	v_add_f32_e32 v102, 1.0, v102
	v_rcp_f32_e32 v104, v104
	v_rcp_f32_e32 v105, v102
	v_lshl_add_u64 v[102:103], s[0:1], 0, v[170:171]
	s_movk_i32 s15, 0x1600
	v_pk_mul_f32 v[98:99], v[98:99], v[106:107]
	v_pk_mul_f32 v[100:101], v[100:101], v[104:105]
	v_mov_b64_e32 v[104:105], s[26:27]
	v_mad_u64_u32 v[104:105], s[26:27], v102, s15, v[104:105]
	v_mad_i32_i24 v105, v103, s15, v105
	v_lshl_add_u64 v[102:103], v[192:193], 1, v[104:105]
	v_cvt_pk_bf16_f32 v98, v98, v99
	v_cvt_pk_bf16_f32 v99, v100, v101
	global_store_dwordx2 v[102:103], v[98:99], off offset:8

.LBB0_971:
	v_cndmask_b32_e64 v19, v19, 0, s[10:11]
	v_cndmask_b32_e64 v18, v18, 0, s[10:11]
	v_cndmask_b32_e64 v21, v21, 0, s[10:11]
	v_cndmask_b32_e64 v20, v20, 0, s[10:11]
	v_pk_fma_f32 v[18:19], v[18:19], v[78:79], v[94:95]
	v_pk_fma_f32 v[20:21], v[20:21], v[80:81], v[96:97]
	v_pk_fma_f32 v[18:19], v[54:55], v[82:83], v[18:19]
	v_pk_fma_f32 v[20:21], v[56:57], v[84:85], v[20:21]
	v_pk_fma_f32 v[18:19], v[62:63], v[90:91], v[18:19]
	v_pk_fma_f32 v[20:21], v[64:65], v[92:93], v[20:21]
	v_mul_f32_e32 v26, 0xbfb8aa3b, v18
	v_mul_f32_e32 v27, 0xbfb8aa3b, v19
	v_mul_f32_e32 v28, 0xbfb8aa3b, v20
	v_mul_f32_e32 v29, 0xbfb8aa3b, v21
	v_exp_f32_e32 v26, v26
	v_exp_f32_e32 v27, v27
	v_exp_f32_e32 v28, v28
	v_exp_f32_e32 v29, v29
	v_cndmask_b32_e64 v25, v25, 0, s[10:11]
	v_cndmask_b32_e64 v24, v24, 0, s[10:11]
	v_cndmask_b32_e64 v23, v23, 0, s[10:11]
	v_cndmask_b32_e64 v22, v22, 0, s[10:11]
	v_add_f32_e32 v26, 1.0, v26
	v_pk_fma_f32 v[22:23], v[22:23], v[66:67], v[70:71]
	v_pk_fma_f32 v[24:25], v[24:25], v[68:69], v[72:73]
	v_add_f32_e32 v27, 1.0, v27
	v_add_f32_e32 v28, 1.0, v28
	v_add_f32_e32 v29, 1.0, v29
	v_rcp_f32_e32 v26, v26
	v_pk_fma_f32 v[24:25], v[44:45], v[52:53], v[24:25]
	v_pk_fma_f32 v[22:23], v[42:43], v[50:51], v[22:23]
	v_rcp_f32_e32 v27, v27
	v_rcp_f32_e32 v28, v28
	v_rcp_f32_e32 v29, v29
	v_readlane_b32 s10, v251, 45
	v_pk_fma_f32 v[22:23], v[58:59], v[46:47], v[22:23]
	v_pk_fma_f32 v[24:25], v[60:61], v[48:49], v[24:25]
	v_readlane_b32 s11, v251, 46
	v_pk_mul_f32 v[20:21], v[24:25], v[20:21]
	v_pk_mul_f32 v[18:19], v[22:23], v[18:19]
	v_lshl_add_u64 v[22:23], s[0:1], 0, v[164:165]
	v_mov_b64_e32 v[24:25], s[10:11]
	s_movk_i32 s15, 0x1600
	v_mad_u64_u32 v[24:25], s[10:11], v22, s15, v[24:25]
	v_pk_mul_f32 v[18:19], v[18:19], v[26:27]
	v_pk_mul_f32 v[20:21], v[20:21], v[28:29]
	v_mad_i32_i24 v25, v23, s15, v25
	v_lshl_add_u64 v[22:23], v[192:193], 1, v[24:25]
	v_cvt_pk_bf16_f32 v18, v18, v19
	v_cvt_pk_bf16_f32 v19, v20, v21
	global_store_dwordx2 v[22:23], v[18:19], off offset:8

.LBB0_974:
	v_mov_b32_e32 v123, v122
	v_mov_b32_e32 v42, v122
	v_mov_b32_e32 v43, v122
	v_pk_mul_f32 v[16:17], v[16:17], v[42:43]
	v_pk_mul_f32 v[14:15], v[14:15], v[122:123]
	v_pk_mul_f32 v[12:13], v[12:13], v[42:43]
	v_pk_mul_f32 v[10:11], v[10:11], v[122:123]
	s_waitcnt lgkmcnt(3)
	v_mov_b32_dpp v26, v34 row_shr:1 row_mask:0xf bank_mask:0xf
	s_waitcnt lgkmcnt(2)
	v_mov_b32_dpp v18, v74 row_shr:1 row_mask:0xf bank_mask:0xf
	s_waitcnt lgkmcnt(1)
	v_mov_b32_dpp v30, v38 row_shr:1 row_mask:0xf bank_mask:0xf
	s_waitcnt lgkmcnt(0)
	v_mov_b32_dpp v22, v86 row_shr:1 row_mask:0xf bank_mask:0xf
	v_mov_b32_dpp v27, v35 row_shr:1 row_mask:0xf bank_mask:0xf
	v_mov_b32_dpp v19, v75 row_shr:1 row_mask:0xf bank_mask:0xf
	v_mov_b32_dpp v31, v39 row_shr:1 row_mask:0xf bank_mask:0xf
	v_mov_b32_dpp v23, v87 row_shr:1 row_mask:0xf bank_mask:0xf
	v_mov_b32_dpp v28, v36 row_shr:1 row_mask:0xf bank_mask:0xf
	v_mov_b32_dpp v20, v76 row_shr:1 row_mask:0xf bank_mask:0xf
	v_mov_b32_dpp v32, v40 row_shr:1 row_mask:0xf bank_mask:0xf
	v_mov_b32_dpp v24, v88 row_shr:1 row_mask:0xf bank_mask:0xf
	v_mov_b32_dpp v29, v37 row_shr:1 row_mask:0xf bank_mask:0xf
	v_mov_b32_dpp v21, v77 row_shr:1 row_mask:0xf bank_mask:0xf
	v_mov_b32_dpp v33, v41 row_shr:1 row_mask:0xf bank_mask:0xf
	v_mov_b32_dpp v25, v89 row_shr:1 row_mask:0xf bank_mask:0xf
	s_and_saveexec_b64 s[10:11], s[54:55]
	s_movk_i32 s54, 0x1600
	s_cbranch_execz .LBB0_976
	v_pk_fma_f32 v[30:31], v[78:79], v[30:31], v[94:95]
	v_pk_fma_f32 v[26:27], v[66:67], v[26:27], v[70:71]
	v_pk_fma_f32 v[30:31], v[82:83], v[22:23], v[30:31]
	v_pk_fma_f32 v[26:27], v[50:51], v[18:19], v[26:27]
	v_pk_fma_f32 v[30:31], v[10:11], v[90:91], v[30:31]
	v_pk_fma_f32 v[26:27], v[14:15], v[46:47], v[26:27]
	v_mul_f32_e32 v42, 0xbfb8aa3b, v30
	v_pk_mul_f32 v[26:27], v[26:27], v[30:31]
	v_mul_f32_e32 v30, 0xbfb8aa3b, v31
	v_exp_f32_e32 v30, v30
	v_pk_fma_f32 v[28:29], v[68:69], v[28:29], v[72:73]
	v_exp_f32_e32 v42, v42
	v_pk_fma_f32 v[28:29], v[52:53], v[20:21], v[28:29]
	v_add_f32_e32 v30, 1.0, v30
	v_rcp_f32_e32 v43, v30
	v_pk_fma_f32 v[30:31], v[80:81], v[32:33], v[96:97]
	v_pk_fma_f32 v[28:29], v[16:17], v[48:49], v[28:29]
	v_pk_fma_f32 v[30:31], v[84:85], v[24:25], v[30:31]
	v_add_f32_e32 v42, 1.0, v42
	v_pk_fma_f32 v[30:31], v[12:13], v[92:93], v[30:31]
	v_rcp_f32_e32 v42, v42
	v_mul_f32_e32 v32, 0xbfb8aa3b, v30
	v_pk_mul_f32 v[28:29], v[28:29], v[30:31]
	v_mul_f32_e32 v30, 0xbfb8aa3b, v31
	v_exp_f32_e32 v32, v32
	v_exp_f32_e32 v30, v30
	v_readlane_b32 s24, v251, 45
	v_readlane_b32 s25, v251, 46
	v_add_f32_e32 v32, 1.0, v32
	v_add_f32_e32 v30, 1.0, v30
	v_rcp_f32_e32 v32, v32
	v_rcp_f32_e32 v33, v30
	v_lshl_add_u64 v[30:31], s[0:1], 0, v[114:115]
	v_pk_mul_f32 v[26:27], v[26:27], v[42:43]
	v_pk_mul_f32 v[28:29], v[28:29], v[32:33]
	v_mov_b64_e32 v[32:33], s[24:25]
	v_mad_u64_u32 v[32:33], s[24:25], v30, s54, v[32:33]
	v_mad_i32_i24 v33, v31, s54, v33
	v_lshl_add_u64 v[30:31], v[192:193], 1, v[32:33]
	v_cvt_pk_bf16_f32 v26, v26, v27
	v_cvt_pk_bf16_f32 v27, v28, v29
	global_store_dwordx2 v[30:31], v[26:27], off offset:8
.LBB0_976:
	s_or_b64 exec, exec, s[10:11]
	v_mov_b32_e32 v125, v124
	v_mov_b32_e32 v26, v124
	v_mov_b32_e32 v27, v124
	v_pk_mul_f32 v[8:9], v[8:9], v[26:27]
	v_pk_mul_f32 v[6:7], v[6:7], v[124:125]
	v_pk_mul_f32 v[4:5], v[4:5], v[26:27]
	v_pk_mul_f32 v[2:3], v[2:3], v[124:125]
	s_and_saveexec_b64 s[10:11], s[40:41]
	s_cbranch_execz .LBB0_978
	v_pk_fma_f32 v[22:23], v[78:79], v[22:23], v[94:95]
	v_pk_fma_f32 v[18:19], v[66:67], v[18:19], v[70:71]
	v_pk_fma_f32 v[22:23], v[10:11], v[82:83], v[22:23]
	v_pk_fma_f32 v[18:19], v[14:15], v[50:51], v[18:19]
	v_pk_fma_f32 v[22:23], v[2:3], v[90:91], v[22:23]
	v_pk_fma_f32 v[18:19], v[6:7], v[46:47], v[18:19]
	v_mul_f32_e32 v26, 0xbfb8aa3b, v22
	v_pk_mul_f32 v[18:19], v[18:19], v[22:23]
	v_mul_f32_e32 v22, 0xbfb8aa3b, v23
	v_exp_f32_e32 v22, v22
	v_pk_fma_f32 v[20:21], v[68:69], v[20:21], v[72:73]
	v_exp_f32_e32 v26, v26
	v_pk_fma_f32 v[20:21], v[16:17], v[52:53], v[20:21]
	v_add_f32_e32 v22, 1.0, v22
	v_rcp_f32_e32 v27, v22
	v_pk_fma_f32 v[22:23], v[80:81], v[24:25], v[96:97]
	v_pk_fma_f32 v[20:21], v[8:9], v[48:49], v[20:21]
	v_pk_fma_f32 v[22:23], v[12:13], v[84:85], v[22:23]
	v_add_f32_e32 v26, 1.0, v26
	v_pk_fma_f32 v[22:23], v[4:5], v[92:93], v[22:23]
	v_rcp_f32_e32 v26, v26
	v_mul_f32_e32 v24, 0xbfb8aa3b, v22
	v_pk_mul_f32 v[20:21], v[20:21], v[22:23]
	v_mul_f32_e32 v22, 0xbfb8aa3b, v23
	v_exp_f32_e32 v24, v24
	v_exp_f32_e32 v22, v22
	v_readlane_b32 s24, v251, 45
	v_readlane_b32 s25, v251, 46
	v_add_f32_e32 v24, 1.0, v24
	v_add_f32_e32 v22, 1.0, v22
	v_rcp_f32_e32 v24, v24
	v_rcp_f32_e32 v25, v22
	v_lshl_add_u64 v[22:23], s[0:1], 0, v[116:117]
	v_pk_mul_f32 v[18:19], v[18:19], v[26:27]
	v_pk_mul_f32 v[20:21], v[20:21], v[24:25]
	v_mov_b64_e32 v[24:25], s[24:25]
	v_mad_u64_u32 v[24:25], s[24:25], v22, s54, v[24:25]
	v_mad_i32_i24 v25, v23, s54, v25
	v_lshl_add_u64 v[22:23], v[192:193], 1, v[24:25]
	v_cvt_pk_bf16_f32 v18, v18, v19
	v_cvt_pk_bf16_f32 v19, v20, v21
	global_store_dwordx2 v[22:23], v[18:19], off offset:8

.LBB0_981:
	v_cndmask_b32_e64 v3, v3, 0, s[12:13]
	v_cndmask_b32_e64 v2, v2, 0, s[12:13]
	v_cndmask_b32_e64 v5, v5, 0, s[12:13]
	v_cndmask_b32_e64 v4, v4, 0, s[12:13]
	v_pk_fma_f32 v[2:3], v[2:3], v[78:79], v[94:95]
	v_pk_fma_f32 v[4:5], v[4:5], v[80:81], v[96:97]
	v_pk_fma_f32 v[2:3], v[38:39], v[82:83], v[2:3]
	v_pk_fma_f32 v[4:5], v[40:41], v[84:85], v[4:5]
	v_pk_fma_f32 v[2:3], v[86:87], v[90:91], v[2:3]
	v_pk_fma_f32 v[4:5], v[88:89], v[92:93], v[4:5]
	v_mul_f32_e32 v10, 0xbfb8aa3b, v2
	v_mul_f32_e32 v11, 0xbfb8aa3b, v3
	v_mul_f32_e32 v12, 0xbfb8aa3b, v4
	v_mul_f32_e32 v13, 0xbfb8aa3b, v5
	v_exp_f32_e32 v10, v10
	v_exp_f32_e32 v11, v11
	v_exp_f32_e32 v12, v12
	v_exp_f32_e32 v13, v13
	v_cndmask_b32_e64 v7, v7, 0, s[12:13]
	v_cndmask_b32_e64 v6, v6, 0, s[12:13]
	v_pk_fma_f32 v[6:7], v[6:7], v[66:67], v[70:71]
	v_cndmask_b32_e64 v9, v9, 0, s[12:13]
	v_cndmask_b32_e64 v8, v8, 0, s[12:13]
	v_pk_fma_f32 v[6:7], v[34:35], v[50:51], v[6:7]
	v_add_f32_e32 v10, 1.0, v10
	v_pk_fma_f32 v[8:9], v[8:9], v[68:69], v[72:73]
	v_pk_fma_f32 v[6:7], v[74:75], v[46:47], v[6:7]
	v_add_f32_e32 v11, 1.0, v11
	v_add_f32_e32 v12, 1.0, v12
	v_add_f32_e32 v13, 1.0, v13
	v_rcp_f32_e32 v10, v10
	v_pk_fma_f32 v[8:9], v[36:37], v[52:53], v[8:9]
	v_rcp_f32_e32 v11, v11
	v_rcp_f32_e32 v12, v12
	v_rcp_f32_e32 v13, v13
	v_pk_mul_f32 v[2:3], v[6:7], v[2:3]
	v_lshl_add_u64 v[6:7], s[0:1], 0, v[120:121]
	v_readlane_b32 s0, v251, 45
	v_pk_fma_f32 v[8:9], v[76:77], v[48:49], v[8:9]
	v_readlane_b32 s1, v251, 46
	v_pk_mul_f32 v[4:5], v[8:9], v[4:5]
	v_pk_mul_f32 v[2:3], v[2:3], v[10:11]
	v_mov_b64_e32 v[8:9], s[0:1]
	v_mad_u64_u32 v[8:9], s[0:1], v6, s54, v[8:9]
	v_pk_mul_f32 v[4:5], v[4:5], v[12:13]
	v_mad_i32_i24 v9, v7, s54, v9
	v_lshl_add_u64 v[6:7], v[192:193], 1, v[8:9]
	v_cvt_pk_bf16_f32 v2, v2, v3
	v_cvt_pk_bf16_f32 v3, v4, v5
	global_store_dwordx2 v[6:7], v[2:3], off offset:8

.LBB0_986:
	v_pk_fma_f32 v[26:27], v[78:79], v[26:27], v[94:95]
	v_pk_fma_f32 v[32:33], v[68:69], v[32:33], v[72:73]
	v_pk_fma_f32 v[26:27], v[82:83], v[104:105], v[26:27]
	v_pk_fma_f32 v[32:33], v[52:53], v[100:101], v[32:33]
	v_pk_fma_f32 v[26:27], v[54:55], v[90:91], v[26:27]
	v_pk_fma_f32 v[28:29], v[80:81], v[28:29], v[96:97]
	v_mul_f32_e32 v100, 0xbfb8aa3b, v27
	v_exp_f32_e32 v100, v100
	v_pk_fma_f32 v[28:29], v[84:85], v[102:103], v[28:29]
	v_pk_fma_f32 v[30:31], v[66:67], v[30:31], v[70:71]
	v_pk_fma_f32 v[28:29], v[56:57], v[92:93], v[28:29]
	v_mul_f32_e32 v104, 0xbfb8aa3b, v26
	v_pk_fma_f32 v[30:31], v[50:51], v[98:99], v[30:31]
	v_add_f32_e32 v98, 1.0, v100
	v_mul_f32_e32 v99, 0xbfb8aa3b, v28
	v_mul_f32_e32 v100, 0xbfb8aa3b, v29
	v_exp_f32_e32 v104, v104
	v_exp_f32_e32 v99, v99
	v_exp_f32_e32 v100, v100
	v_rcp_f32_e32 v103, v98
	v_add_f32_e32 v102, 1.0, v104
	v_add_f32_e32 v98, 1.0, v99
	v_add_f32_e32 v99, 1.0, v100
	v_rcp_f32_e32 v102, v102
	v_rcp_f32_e32 v98, v98
	v_rcp_f32_e32 v99, v99
	v_readlane_b32 s26, v251, 45
	v_pk_fma_f32 v[32:33], v[44:45], v[48:49], v[32:33]
	v_pk_fma_f32 v[30:31], v[42:43], v[46:47], v[30:31]
	v_readlane_b32 s27, v251, 46
	v_pk_mul_f32 v[28:29], v[32:33], v[28:29]
	v_pk_mul_f32 v[26:27], v[30:31], v[26:27]
	v_lshl_add_u64 v[30:31], s[0:1], 0, v[162:163]
	v_mov_b64_e32 v[32:33], s[26:27]
	s_movk_i32 s15, 0x1600
	v_mad_u64_u32 v[32:33], s[26:27], v30, s15, v[32:33]
	v_pk_mul_f32 v[26:27], v[26:27], v[102:103]
	v_pk_mul_f32 v[28:29], v[28:29], v[98:99]
	v_mad_i32_i24 v33, v31, s15, v33
	v_lshl_add_u64 v[30:31], v[192:193], 1, v[32:33]
	v_cvt_pk_bf16_f32 v26, v26, v27
	v_cvt_pk_bf16_f32 v27, v28, v29
	global_store_dwordx2 v[30:31], v[26:27], off offset:8
	s_or_b64 exec, exec, s[24:25]
	s_and_saveexec_b64 s[24:25], s[92:93]
	s_cbranch_execnz .LBB0_971
	s_branch .LBB0_972

.LBB0_988:
	v_pk_fma_f32 v[10:11], v[78:79], v[10:11], v[94:95]
	v_pk_fma_f32 v[16:17], v[68:69], v[16:17], v[72:73]
	v_pk_fma_f32 v[10:11], v[82:83], v[24:25], v[10:11]
	v_pk_fma_f32 v[16:17], v[52:53], v[20:21], v[16:17]
	v_pk_fma_f32 v[10:11], v[38:39], v[90:91], v[10:11]
	v_pk_fma_f32 v[12:13], v[80:81], v[12:13], v[96:97]
	v_mul_f32_e32 v20, 0xbfb8aa3b, v11
	v_exp_f32_e32 v20, v20
	v_pk_fma_f32 v[12:13], v[84:85], v[22:23], v[12:13]
	v_pk_fma_f32 v[14:15], v[66:67], v[14:15], v[70:71]
	v_pk_fma_f32 v[12:13], v[40:41], v[92:93], v[12:13]
	v_mul_f32_e32 v24, 0xbfb8aa3b, v10
	v_pk_fma_f32 v[14:15], v[50:51], v[18:19], v[14:15]
	v_add_f32_e32 v18, 1.0, v20
	v_mul_f32_e32 v19, 0xbfb8aa3b, v12
	v_mul_f32_e32 v20, 0xbfb8aa3b, v13
	v_exp_f32_e32 v24, v24
	v_exp_f32_e32 v19, v19
	v_exp_f32_e32 v20, v20
	v_rcp_f32_e32 v23, v18
	v_add_f32_e32 v22, 1.0, v24
	v_add_f32_e32 v18, 1.0, v19
	v_add_f32_e32 v19, 1.0, v20
	v_rcp_f32_e32 v22, v22
	v_rcp_f32_e32 v18, v18
	v_rcp_f32_e32 v19, v19
	v_readlane_b32 s24, v251, 45
	v_pk_fma_f32 v[16:17], v[36:37], v[48:49], v[16:17]
	v_pk_fma_f32 v[14:15], v[34:35], v[46:47], v[14:15]
	v_readlane_b32 s25, v251, 46
	v_pk_mul_f32 v[12:13], v[16:17], v[12:13]
	v_pk_mul_f32 v[10:11], v[14:15], v[10:11]
	v_lshl_add_u64 v[14:15], s[0:1], 0, v[118:119]
	v_mov_b64_e32 v[16:17], s[24:25]
	v_mad_u64_u32 v[16:17], s[24:25], v14, s54, v[16:17]
	v_pk_mul_f32 v[10:11], v[10:11], v[22:23]
	v_pk_mul_f32 v[12:13], v[12:13], v[18:19]
	v_mad_i32_i24 v17, v15, s54, v17
	v_lshl_add_u64 v[14:15], v[192:193], 1, v[16:17]
	v_cvt_pk_bf16_f32 v10, v10, v11
	v_cvt_pk_bf16_f32 v11, v12, v13
	global_store_dwordx2 v[14:15], v[10:11], off offset:8
	s_or_b64 exec, exec, s[10:11]
	s_and_saveexec_b64 s[10:11], s[48:49]
	s_cbranch_execnz .LBB0_981
	s_branch .LBB0_982
